# down-GEMM K-loop: last LDS-DMA family also in SGPR-base form (base +0x80 / -0x80 by SALU)
# baseline (speedup 1.0000x reference)
; #define PG8_STAGE(bufoff, gbase, voff) do { _Pragma("unroll") for (int _i = 0; _i < 2; ++_i) \
;         __builtin_amdgcn_global_load_lds((const unsigned*)((const char*)(gbase) + (voff)[_i]), (PG8_LAS unsigned*)(lds + (bufoff) + ldsw + _i * 8192), 16, 0, 0); } while (0)
; #define PG8_LDA(dst, b, h) do { _Pragma("unroll") for (int m = 0; m < 4; ++m) _Pragma("unroll") for (int k = 0; k < 2; ++k) dst[m][k] = *(const PG8_LAS bf16x8*)(lds + PG8_SA(b, h) + aoff + m * 2048 + k * 1024); } while (0)
; #define PG8_LDB(dst, b, h) do { _Pragma("unroll") for (int n = 0; n < 2; ++n) _Pragma("unroll") for (int k = 0; k < 2; ++k) dst[n][k] = *(const PG8_LAS bf16x8*)(lds + PG8_SB(b, h) + boff + n * 2048 + k * 1024); } while (0)
; #define PG8_MMA(ai, bj, At, Bt) do { __builtin_amdgcn_s_setprio(1); _Pragma("unroll") for (int m = 0; m < 4; ++m) _Pragma("unroll") for (int n = 0; n < 2; ++n) _Pragma("unroll") for (int k = 0; k < 2; ++k) \
;         acc[ai][bj][m][n] = __builtin_amdgcn_mfma_f32_16x16x32_bf16(Bt[n][k], At[m][k], acc[ai][bj][m][n], 0, 0, 0); __builtin_amdgcn_s_setprio(0); } while (0)
; #define PG8_WAIT_V(n) asm volatile("s_waitcnt vmcnt(" #n ")" ::: "memory")
; #define PG8_WAIT_L(n) asm volatile("s_waitcnt lgkmcnt(" #n ")" ::: "memory")
; template <class Epi, class Sched, bool ALIGN_EPI = false, bool SP2 = false>
; __device__ __forceinline__ void gemm_phase(PG8_LAS unsigned char* lds, const Gemm g, const Sched& S, const Epi& E, int tid_in) {
;     ...
;             const bool last = (t == nt - 2);
;             const char* a1 = cA + (size_t)(t + 1) * kstep;
;             const char* a2 = last ? nA : cA + (size_t)(t + 2) * kstep; const char* b2 = last ? nB : cB + (size_t)(t + 2) * kstep;
;             const char* a3 = a2 + kstep; const char* b3 = b2 + kstep;
;             if (last && has_next) S.a_ready(nxt);
;             if constexpr (SP2) {
;             PG8_LDB(B0, 0, 0); PG8_LDB(B1, 0, 1); PG8_SCHED; PG8_LDA(At, 0, 0); PG8_STAGE(PG8_SA(1, 1), a1 + hstepA, voffA);
;             PG8_WAIT_V(8); PG8_WAIT_L(0); PG8_BAR; PG8_MMA(0, 0, At, B0); PG8_MMA(0, 1, At, B1); PG8_BAR; PG8_SCHED;
;             PG8_LDA(At, 0, 1); PG8_STAGE(PG8_SB(0, 0), b2, voffB); PG8_STAGE(PG8_SB(0, 1), b2 + hstep, voffB); PG8_STAGE(PG8_SA(0, 0), a2, voffA);
;             PG8_WAIT_V(8); PG8_WAIT_L(0); PG8_BAR; PG8_MMA(1, 0, At, B0); PG8_MMA(1, 1, At, B1); PG8_BAR; PG8_SCHED;
.LBB0_1479:
	s_add_u32 s14, s12, 0x100
	s_addc_u32 s15, s13, 0
	s_add_i32 s56, 0, 0x10000
	s_cmp_eq_u32 s55, 40
	s_cselect_b32 s25, s11, s15
	s_cselect_b32 s24, s10, s14
	s_cselect_b32 s21, s19, s45
	s_cselect_b32 s20, s18, s44
	s_add_i32 s57, 0, 0x14000
	v_add_u32_e32 v124, s56, v226
	v_add_u32_e32 v140, s57, v226
	ds_read_b128 v[112:115], v124
	ds_read_b128 v[116:119], v124 offset:1024
	ds_read_b128 v[120:123], v124 offset:2048
	ds_read_b128 v[124:127], v124 offset:3072
	ds_read_b128 v[128:131], v140
	ds_read_b128 v[132:135], v140 offset:1024
	ds_read_b128 v[136:139], v140 offset:2048
	ds_read_b128 v[140:143], v140 offset:3072
	s_add_i32 m0, s31, 0xc000
	ds_read_b128 v[144:147], v227
	ds_read_b128 v[148:151], v227 offset:1024
	ds_read_b128 v[152:155], v227 offset:2048
	ds_read_b128 v[156:159], v227 offset:3072
	ds_read_b128 v[176:179], v227 offset:4096
	ds_read_b128 v[180:183], v227 offset:5120
	ds_read_b128 v[208:211], v227 offset:6144
	ds_read_b128 v[212:215], v227 offset:7168
	global_load_lds_dwordx4 v206, s[12:13]
	s_add_i32 m0, s31, 0xe000
	s_nop 0
	global_load_lds_dwordx4 v204, s[12:13]
	s_waitcnt vmcnt(8)
	s_waitcnt lgkmcnt(0)
	s_barrier
	s_setprio 1
	s_waitcnt lgkmcnt(0)
	v_mfma_f32_16x16x32_bf16 v[172:175], v[112:115], v[144:147], v[172:175]
	v_mfma_f32_16x16x32_bf16 v[168:171], v[120:123], v[144:147], v[168:171]
	v_mfma_f32_16x16x32_bf16 v[108:111], v[112:115], v[152:155], v[108:111]
	v_mfma_f32_16x16x32_bf16 v[104:107], v[120:123], v[152:155], v[104:107]
	v_mfma_f32_16x16x32_bf16 v[92:95], v[112:115], v[176:179], v[92:95]
	v_mfma_f32_16x16x32_bf16 v[88:91], v[120:123], v[176:179], v[88:91]
	v_mfma_f32_16x16x32_bf16 v[76:79], v[112:115], v[208:211], v[76:79]
	v_mfma_f32_16x16x32_bf16 v[72:75], v[120:123], v[208:211], v[72:75]
	v_mfma_f32_16x16x32_bf16 v[172:175], v[116:119], v[148:151], v[172:175]
	v_mfma_f32_16x16x32_bf16 v[168:171], v[124:127], v[148:151], v[168:171]
	v_mfma_f32_16x16x32_bf16 v[108:111], v[116:119], v[156:159], v[108:111]
	v_mfma_f32_16x16x32_bf16 v[104:107], v[124:127], v[156:159], v[104:107]
	v_mfma_f32_16x16x32_bf16 v[92:95], v[116:119], v[180:183], v[92:95]
	v_mfma_f32_16x16x32_bf16 v[88:91], v[124:127], v[180:183], v[88:91]
	v_mfma_f32_16x16x32_bf16 v[76:79], v[116:119], v[212:215], v[76:79]
	v_mfma_f32_16x16x32_bf16 v[72:75], v[124:127], v[212:215], v[72:75]
	s_setprio 0
	s_setprio 1
	v_mfma_f32_16x16x32_bf16 v[164:167], v[128:131], v[144:147], v[164:167]
	v_mfma_f32_16x16x32_bf16 v[100:103], v[128:131], v[152:155], v[100:103]
	v_mfma_f32_16x16x32_bf16 v[96:99], v[136:139], v[152:155], v[96:99]
	v_mfma_f32_16x16x32_bf16 v[84:87], v[128:131], v[176:179], v[84:87]
	v_mfma_f32_16x16x32_bf16 v[80:83], v[136:139], v[176:179], v[80:83]
	v_mfma_f32_16x16x32_bf16 v[68:71], v[128:131], v[208:211], v[68:71]
	v_mfma_f32_16x16x32_bf16 v[64:67], v[136:139], v[208:211], v[64:67]
	v_mfma_f32_16x16x32_bf16 v[164:167], v[132:135], v[148:151], v[164:167]
	v_mfma_f32_16x16x32_bf16 v[144:147], v[136:139], v[144:147], v[160:163]
	v_mfma_f32_16x16x32_bf16 v[100:103], v[132:135], v[156:159], v[100:103]
	v_mfma_f32_16x16x32_bf16 v[96:99], v[140:143], v[156:159], v[96:99]
	v_mfma_f32_16x16x32_bf16 v[84:87], v[132:135], v[180:183], v[84:87]
	v_mfma_f32_16x16x32_bf16 v[80:83], v[140:143], v[180:183], v[80:83]
	v_mfma_f32_16x16x32_bf16 v[68:71], v[132:135], v[212:215], v[68:71]
	v_mfma_f32_16x16x32_bf16 v[64:67], v[140:143], v[212:215], v[64:67]
	v_mfma_f32_16x16x32_bf16 v[144:147], v[140:143], v[148:151], v[144:147]
	s_setprio 0
	s_barrier
	s_add_i32 s12, s56, s30
	s_mov_b64 s[100:101], s[20:21]
	s_mov_b32 m0, s12
	ds_read_b128 v[148:151], v227 offset:16384
	ds_read_b128 v[152:155], v227 offset:17408
	ds_read_b128 v[156:159], v227 offset:18432
	ds_read_b128 v[160:163], v227 offset:19456
	ds_read_b128 v[176:179], v227 offset:20480
	ds_read_b128 v[180:183], v227 offset:21504
	ds_read_b128 v[208:211], v227 offset:22528
	ds_read_b128 v[212:215], v227 offset:23552
	global_load_lds_dwordx4 v190, s[100:101]
	s_add_i32 m0, s12, 0x2000
	s_add_u32 s12, s20, 0xb0000
	s_addc_u32 s13, s21, 0
	s_add_i32 s56, s57, s30
	global_load_lds_dwordx4 v184, s[100:101]
	s_mov_b32 m0, s56
	s_nop 0
	global_load_lds_dwordx4 v190, s[12:13]
	s_add_i32 m0, s56, 0x2000
	s_nop 0
	global_load_lds_dwordx4 v184, s[12:13]
	s_mov_b32 m0, s31
	s_nop 0
	global_load_lds_dwordx4 v188, s[24:25]
	s_mov_b32 m0, s34
	s_nop 0
	global_load_lds_dwordx4 v186, s[24:25]
	s_waitcnt vmcnt(8)
	s_waitcnt lgkmcnt(0)
	s_barrier
	s_setprio 1
	s_waitcnt lgkmcnt(0)
	v_mfma_f32_16x16x32_bf16 v[60:63], v[112:115], v[148:151], v[60:63]
	v_mfma_f32_16x16x32_bf16 v[56:59], v[120:123], v[148:151], v[56:59]
	v_mfma_f32_16x16x32_bf16 v[44:47], v[112:115], v[156:159], v[44:47]
	v_mfma_f32_16x16x32_bf16 v[40:43], v[120:123], v[156:159], v[40:43]
	v_mfma_f32_16x16x32_bf16 v[28:31], v[112:115], v[176:179], v[28:31]
	v_mfma_f32_16x16x32_bf16 v[24:27], v[120:123], v[176:179], v[24:27]
	v_mfma_f32_16x16x32_bf16 v[12:15], v[112:115], v[208:211], v[12:15]
	v_mfma_f32_16x16x32_bf16 v[8:11], v[120:123], v[208:211], v[8:11]
	v_mfma_f32_16x16x32_bf16 v[60:63], v[116:119], v[152:155], v[60:63]
	v_mfma_f32_16x16x32_bf16 v[56:59], v[124:127], v[152:155], v[56:59]
	v_mfma_f32_16x16x32_bf16 v[44:47], v[116:119], v[160:163], v[44:47]
	v_mfma_f32_16x16x32_bf16 v[40:43], v[124:127], v[160:163], v[40:43]
	v_mfma_f32_16x16x32_bf16 v[28:31], v[116:119], v[180:183], v[28:31]
	v_mfma_f32_16x16x32_bf16 v[24:27], v[124:127], v[180:183], v[24:27]
	v_mfma_f32_16x16x32_bf16 v[12:15], v[116:119], v[212:215], v[12:15]
	v_mfma_f32_16x16x32_bf16 v[8:11], v[124:127], v[212:215], v[8:11]
	s_setprio 0
	s_setprio 1
	v_mfma_f32_16x16x32_bf16 v[52:55], v[128:131], v[148:151], v[52:55]
	v_mfma_f32_16x16x32_bf16 v[48:51], v[136:139], v[148:151], v[48:51]
	v_mfma_f32_16x16x32_bf16 v[36:39], v[128:131], v[156:159], v[36:39]
	v_mfma_f32_16x16x32_bf16 v[32:35], v[136:139], v[156:159], v[32:35]
	v_mfma_f32_16x16x32_bf16 v[20:23], v[128:131], v[176:179], v[20:23]
	v_mfma_f32_16x16x32_bf16 v[16:19], v[136:139], v[176:179], v[16:19]
	v_mfma_f32_16x16x32_bf16 v[4:7], v[128:131], v[208:211], v[4:7]
	v_mfma_f32_16x16x32_bf16 v[0:3], v[136:139], v[208:211], v[0:3]
	v_mfma_f32_16x16x32_bf16 v[52:55], v[132:135], v[152:155], v[52:55]
	v_mfma_f32_16x16x32_bf16 v[48:51], v[140:143], v[152:155], v[48:51]
	v_mfma_f32_16x16x32_bf16 v[36:39], v[132:135], v[160:163], v[36:39]
	v_mfma_f32_16x16x32_bf16 v[32:35], v[140:143], v[160:163], v[32:35]
	v_mfma_f32_16x16x32_bf16 v[20:23], v[132:135], v[180:183], v[20:23]
	v_mfma_f32_16x16x32_bf16 v[16:19], v[140:143], v[180:183], v[16:19]
	v_mfma_f32_16x16x32_bf16 v[4:7], v[132:135], v[212:215], v[4:7]
	v_mfma_f32_16x16x32_bf16 v[0:3], v[140:143], v[212:215], v[0:3]
	s_setprio 0
	s_barrier
; #define PG8_STAGE(bufoff, gbase, voff) do { _Pragma("unroll") for (int _i = 0; _i < 2; ++_i) \
;         __builtin_amdgcn_global_load_lds((const unsigned*)((const char*)(gbase) + (voff)[_i]), (PG8_LAS unsigned*)(lds + (bufoff) + ldsw + _i * 8192), 16, 0, 0); } while (0)
; #define PG8_LDA(dst, b, h) do { _Pragma("unroll") for (int m = 0; m < 4; ++m) _Pragma("unroll") for (int k = 0; k < 2; ++k) dst[m][k] = *(const PG8_LAS bf16x8*)(lds + PG8_SA(b, h) + aoff + m * 2048 + k * 1024); } while (0)
; #define PG8_LDB(dst, b, h) do { _Pragma("unroll") for (int n = 0; n < 2; ++n) _Pragma("unroll") for (int k = 0; k < 2; ++k) dst[n][k] = *(const PG8_LAS bf16x8*)(lds + PG8_SB(b, h) + boff + n * 2048 + k * 1024); } while (0)
; #define PG8_MMA(ai, bj, At, Bt) do { __builtin_amdgcn_s_setprio(1); _Pragma("unroll") for (int m = 0; m < 4; ++m) _Pragma("unroll") for (int n = 0; n < 2; ++n) _Pragma("unroll") for (int k = 0; k < 2; ++k) \
;         acc[ai][bj][m][n] = __builtin_amdgcn_mfma_f32_16x16x32_bf16(Bt[n][k], At[m][k], acc[ai][bj][m][n], 0, 0, 0); __builtin_amdgcn_s_setprio(0); } while (0)
; #define PG8_WAIT_V(n) asm volatile("s_waitcnt vmcnt(" #n ")" ::: "memory")
; #define PG8_WAIT_L(n) asm volatile("s_waitcnt lgkmcnt(" #n ")" ::: "memory")
; #define PG8_BAR __builtin_amdgcn_s_barrier()
; #define PG8_SCHED __builtin_amdgcn_sched_barrier(0)
; template <class Epi, class Sched, bool ALIGN_EPI = false, bool SP2 = false>
; __device__ __forceinline__ void gemm_phase(PG8_LAS unsigned char* lds, const Gemm g, const Sched& S, const Epi& E, int tid_in) {
;     ...
;             PG8_LDB(B0, 1, 0); PG8_LDB(B1, 1, 1); PG8_SCHED; PG8_LDA(At, 1, 0); PG8_STAGE(PG8_SA(0, 1), a2 + hstepA, voffA);
;             PG8_WAIT_V(8); PG8_WAIT_L(0); PG8_BAR; PG8_MMA(0, 0, At, B0); PG8_MMA(0, 1, At, B1); PG8_BAR; PG8_SCHED;
;             PG8_LDA(At, 1, 1); PG8_STAGE(PG8_SB(1, 0), b3, voffB); PG8_STAGE(PG8_SB(1, 1), b3 + hstep, voffB); PG8_STAGE(PG8_SA(1, 0), a3, voffA);
;             PG8_WAIT_V(8); PG8_WAIT_L(0); PG8_BAR; PG8_MMA(1, 0, At, B0); PG8_MMA(1, 1, At, B1); PG8_BAR; PG8_SCHED;
;     ...
;         if constexpr (ALIGN_EPI) { if (wr == 0) PG8_BAR; }
	s_add_i32 s56, 0, 0x18000
	s_add_i32 s57, 0, 0x1c000
	v_add_u32_e32 v124, s56, v226
	v_add_u32_e32 v140, s57, v226
	ds_read_b128 v[112:115], v124
	ds_read_b128 v[116:119], v124 offset:1024
	ds_read_b128 v[120:123], v124 offset:2048
	ds_read_b128 v[124:127], v124 offset:3072
	ds_read_b128 v[128:131], v140
	ds_read_b128 v[132:135], v140 offset:1024
	ds_read_b128 v[136:139], v140 offset:2048
	ds_read_b128 v[140:143], v140 offset:3072
	s_add_u32 s12, s24, 0xb0000
	s_addc_u32 s13, s25, 0
	s_mov_b32 m0, s35
	ds_read_b128 v[148:151], v227 offset:32768
	ds_read_b128 v[152:155], v227 offset:33792
	ds_read_b128 v[156:159], v227 offset:34816
	ds_read_b128 v[176:179], v227 offset:35840
	ds_read_b128 v[180:183], v227 offset:36864
	ds_read_b128 v[208:211], v227 offset:37888
	ds_read_b128 v[212:215], v227 offset:38912
	ds_read_b128 v[216:219], v227 offset:39936
	global_load_lds_dwordx4 v188, s[12:13]
	s_mov_b32 m0, s46
	s_nop 0
	global_load_lds_dwordx4 v186, s[12:13]
	s_waitcnt vmcnt(8)
	s_waitcnt lgkmcnt(0)
	s_barrier
	s_setprio 1
	s_waitcnt lgkmcnt(0)
	v_mfma_f32_16x16x32_bf16 v[160:163], v[112:115], v[148:151], v[172:175]
	v_mfma_f32_16x16x32_bf16 v[172:175], v[116:119], v[152:155], v[160:163]
	v_mfma_f32_16x16x32_bf16 v[160:163], v[120:123], v[148:151], v[168:171]
	v_mfma_f32_16x16x32_bf16 v[108:111], v[112:115], v[156:159], v[108:111]
	v_mfma_f32_16x16x32_bf16 v[104:107], v[120:123], v[156:159], v[104:107]
	v_mfma_f32_16x16x32_bf16 v[92:95], v[112:115], v[180:183], v[92:95]
	v_mfma_f32_16x16x32_bf16 v[88:91], v[120:123], v[180:183], v[88:91]
	v_mfma_f32_16x16x32_bf16 v[76:79], v[112:115], v[212:215], v[76:79]
	v_mfma_f32_16x16x32_bf16 v[72:75], v[120:123], v[212:215], v[72:75]
	v_mfma_f32_16x16x32_bf16 v[168:171], v[124:127], v[152:155], v[160:163]
	v_mfma_f32_16x16x32_bf16 v[108:111], v[116:119], v[176:179], v[108:111]
	v_mfma_f32_16x16x32_bf16 v[104:107], v[124:127], v[176:179], v[104:107]
	v_mfma_f32_16x16x32_bf16 v[92:95], v[116:119], v[208:211], v[92:95]
	v_mfma_f32_16x16x32_bf16 v[88:91], v[124:127], v[208:211], v[88:91]
	v_mfma_f32_16x16x32_bf16 v[76:79], v[116:119], v[216:219], v[76:79]
	v_mfma_f32_16x16x32_bf16 v[72:75], v[124:127], v[216:219], v[72:75]
	s_setprio 0
	s_setprio 1
	v_mfma_f32_16x16x32_bf16 v[160:163], v[128:131], v[148:151], v[164:167]
	v_mfma_f32_16x16x32_bf16 v[144:147], v[136:139], v[148:151], v[144:147]
	v_mfma_f32_16x16x32_bf16 v[100:103], v[128:131], v[156:159], v[100:103]
	v_mfma_f32_16x16x32_bf16 v[96:99], v[136:139], v[156:159], v[96:99]
	v_mfma_f32_16x16x32_bf16 v[84:87], v[128:131], v[180:183], v[84:87]
	v_mfma_f32_16x16x32_bf16 v[80:83], v[136:139], v[180:183], v[80:83]
	v_mfma_f32_16x16x32_bf16 v[68:71], v[128:131], v[212:215], v[68:71]
	v_mfma_f32_16x16x32_bf16 v[64:67], v[136:139], v[212:215], v[64:67]
	v_mfma_f32_16x16x32_bf16 v[164:167], v[132:135], v[152:155], v[160:163]
	v_mfma_f32_16x16x32_bf16 v[160:163], v[140:143], v[152:155], v[144:147]
	v_mfma_f32_16x16x32_bf16 v[100:103], v[132:135], v[176:179], v[100:103]
	v_mfma_f32_16x16x32_bf16 v[96:99], v[140:143], v[176:179], v[96:99]
	v_mfma_f32_16x16x32_bf16 v[84:87], v[132:135], v[208:211], v[84:87]
	v_mfma_f32_16x16x32_bf16 v[80:83], v[140:143], v[208:211], v[80:83]
	v_mfma_f32_16x16x32_bf16 v[68:71], v[132:135], v[216:219], v[68:71]
	v_mfma_f32_16x16x32_bf16 v[64:67], v[140:143], v[216:219], v[64:67]
	s_setprio 0
	s_barrier
	s_add_i32 s12, s56, s30
	s_mov_b32 m0, s12
	ds_read_b128 v[144:147], v227 offset:49152
	ds_read_b128 v[148:151], v227 offset:50176
	ds_read_b128 v[152:155], v227 offset:51200
	ds_read_b128 v[156:159], v227 offset:52224
	ds_read_b128 v[176:179], v227 offset:53248
	ds_read_b128 v[180:183], v227 offset:54272
	ds_read_b128 v[208:211], v227 offset:55296
	ds_read_b128 v[212:215], v227 offset:56320
	s_add_u32 s100, s100, 0x80
	s_addc_u32 s101, s101, 0
	global_load_lds_dwordx4 v190, s[100:101]
	s_add_i32 m0, s12, 0x2000
	s_add_u32 s12, s20, 0xb0080
	s_addc_u32 s13, s21, 0
	s_add_i32 s20, s57, s30
	global_load_lds_dwordx4 v184, s[100:101]
	s_mov_b32 m0, s20
	s_nop 0
	global_load_lds_dwordx4 v190, s[12:13]
	s_add_i32 m0, s20, 0x2000
	s_nop 0
	global_load_lds_dwordx4 v184, s[12:13]
	s_mov_b32 m0, s49
	s_nop 0
	s_add_u32 s24, s24, 0x80
	s_addc_u32 s25, s25, 0
	global_load_lds_dwordx4 v188, s[24:25]
	s_mov_b32 m0, s50
	s_nop 0
	global_load_lds_dwordx4 v186, s[24:25]
	s_sub_u32 s24, s24, 0x80
	s_subb_u32 s25, s25, 0
	s_waitcnt vmcnt(8)
	s_waitcnt lgkmcnt(0)
	s_barrier
	s_setprio 1
	s_waitcnt lgkmcnt(0)
	v_mfma_f32_16x16x32_bf16 v[60:63], v[112:115], v[144:147], v[60:63]
	v_mfma_f32_16x16x32_bf16 v[56:59], v[120:123], v[144:147], v[56:59]
	v_mfma_f32_16x16x32_bf16 v[44:47], v[112:115], v[152:155], v[44:47]
	v_mfma_f32_16x16x32_bf16 v[40:43], v[120:123], v[152:155], v[40:43]
	v_mfma_f32_16x16x32_bf16 v[28:31], v[112:115], v[176:179], v[28:31]
	v_mfma_f32_16x16x32_bf16 v[24:27], v[120:123], v[176:179], v[24:27]
	v_mfma_f32_16x16x32_bf16 v[12:15], v[112:115], v[208:211], v[12:15]
	v_mfma_f32_16x16x32_bf16 v[8:11], v[120:123], v[208:211], v[8:11]
	v_mfma_f32_16x16x32_bf16 v[60:63], v[116:119], v[148:151], v[60:63]
	v_mfma_f32_16x16x32_bf16 v[56:59], v[124:127], v[148:151], v[56:59]
	v_mfma_f32_16x16x32_bf16 v[44:47], v[116:119], v[156:159], v[44:47]
	v_mfma_f32_16x16x32_bf16 v[40:43], v[124:127], v[156:159], v[40:43]
	v_mfma_f32_16x16x32_bf16 v[28:31], v[116:119], v[180:183], v[28:31]
	v_mfma_f32_16x16x32_bf16 v[24:27], v[124:127], v[180:183], v[24:27]
	v_mfma_f32_16x16x32_bf16 v[12:15], v[116:119], v[212:215], v[12:15]
	v_mfma_f32_16x16x32_bf16 v[8:11], v[124:127], v[212:215], v[8:11]
	s_setprio 0
	s_setprio 1
	v_mfma_f32_16x16x32_bf16 v[52:55], v[128:131], v[144:147], v[52:55]
	v_mfma_f32_16x16x32_bf16 v[48:51], v[136:139], v[144:147], v[48:51]
	v_mfma_f32_16x16x32_bf16 v[36:39], v[128:131], v[152:155], v[36:39]
	v_mfma_f32_16x16x32_bf16 v[32:35], v[136:139], v[152:155], v[32:35]
	v_mfma_f32_16x16x32_bf16 v[20:23], v[128:131], v[176:179], v[20:23]
	v_mfma_f32_16x16x32_bf16 v[16:19], v[136:139], v[176:179], v[16:19]
	v_mfma_f32_16x16x32_bf16 v[4:7], v[128:131], v[208:211], v[4:7]
	v_mfma_f32_16x16x32_bf16 v[0:3], v[136:139], v[208:211], v[0:3]
	v_mfma_f32_16x16x32_bf16 v[52:55], v[132:135], v[148:151], v[52:55]
	v_mfma_f32_16x16x32_bf16 v[48:51], v[140:143], v[148:151], v[48:51]
	v_mfma_f32_16x16x32_bf16 v[36:39], v[132:135], v[156:159], v[36:39]
	v_mfma_f32_16x16x32_bf16 v[32:35], v[140:143], v[156:159], v[32:35]
	v_mfma_f32_16x16x32_bf16 v[20:23], v[132:135], v[180:183], v[20:23]
	v_mfma_f32_16x16x32_bf16 v[16:19], v[140:143], v[180:183], v[16:19]
	v_mfma_f32_16x16x32_bf16 v[4:7], v[132:135], v[212:215], v[4:7]
	v_mfma_f32_16x16x32_bf16 v[0:3], v[140:143], v[212:215], v[0:3]
	s_setprio 0
	s_barrier
	s_add_i32 s55, s55, 2
	s_add_u32 s44, s44, 0x100
	s_addc_u32 s45, s45, 0
	s_cmp_gt_u32 s55, 41
	s_mov_b64 s[12:13], s[14:15]
	s_cbranch_scc0 .LBB0_1479
	s_and_b64 vcc, exec, s[8:9]
	s_cbranch_vccz .LBB0_1482
	s_barrier
